# mixers: bias-table load with all 8 loads in flight (was 4 serialized pairs)
# speedup vs baseline: 1.0059x; 1.0059x over previous
.LBB0_333:
	s_andn2_b64 vcc, exec, s[24:25]
	s_cbranch_vccnz .LBB0_407
	v_mov_b32_e32 v34, v244
	v_readlane_b32 s24, v254, 58
	v_readlane_b32 s50, v255, 40
	v_readlane_b32 s51, v255, 41
	s_nop 3
	s_mul_i32 s26, s24, 0x744
	s_add_u32 s50, s50, s26
	s_addc_u32 s51, s51, 0
	s_mul_i32 s0, s24, 0xa00
	s_add_i32 s26, s0, 0x100
	v_lshlrev_b32_e32 v0, 2, v34
	s_waitcnt vmcnt(0)
	global_load_dword v1, v0, s[50:51]
	global_load_dword v2, v0, s[50:51] offset:256
	global_load_dword v3, v0, s[50:51] offset:512
	global_load_dword v4, v0, s[50:51] offset:768
	global_load_dword v5, v0, s[50:51] offset:1024
	global_load_dword v6, v0, s[50:51] offset:1280
	global_load_dword v7, v0, s[50:51] offset:1536
	v_cmp_gt_u32_e32 vcc, 17, v34
	s_and_saveexec_b64 s[24:25], vcc
	global_load_dword v8, v0, s[50:51] offset:1792
	s_or_b64 exec, exec, s[24:25]
	v_add_u32_e32 v9, s26, v0
	s_waitcnt vmcnt(0)
	v_mul_f32_e32 v1, 0x3fb8aa3b, v1
	v_mul_f32_e32 v2, 0x3fb8aa3b, v2
	v_mul_f32_e32 v3, 0x3fb8aa3b, v3
	v_mul_f32_e32 v4, 0x3fb8aa3b, v4
	v_mul_f32_e32 v5, 0x3fb8aa3b, v5
	v_mul_f32_e32 v6, 0x3fb8aa3b, v6
	v_mul_f32_e32 v7, 0x3fb8aa3b, v7
	v_mul_f32_e32 v8, 0x3fb8aa3b, v8
	ds_write_b32 v9, v1
	ds_write_b32 v9, v2 offset:256
	ds_write_b32 v9, v3 offset:512
	ds_write_b32 v9, v4 offset:768
	ds_write_b32 v9, v5 offset:1024
	ds_write_b32 v9, v6 offset:1280
	ds_write_b32 v9, v7 offset:1536
	s_and_saveexec_b64 s[24:25], vcc
	ds_write_b32 v9, v8 offset:1792
